# attention O epilogue: batched rcp/mul + DPP neighbor exchange instead of 64 serial ds_bpermute round trips; single exec mask for the 64 stores
# speedup vs baseline: 1.0033x; 1.0033x over previous
.LBB0_243:
	s_waitcnt vmcnt(8)
	s_waitcnt vmcnt(9)
	ds_write_b128 v213, v[104:107] offset:32768
	s_waitcnt vmcnt(8)
	ds_write_b128 v213, v[108:111] offset:40960
	s_and_saveexec_b64 s[4:5], s[0:1]
	ds_write_b32 v214, v112
	s_or_b64 exec, exec, s[4:5]
	s_waitcnt lgkmcnt(0)
	ds_read_b128 v[76:79], v212
	s_ashr_i32 s71, s70, 31
	ds_read_b128 v[72:75], v212 offset:32
	ds_read_b128 v[68:71], v212 offset:64
	ds_read_b128 v[64:67], v212 offset:96
	s_lshl_b64 s[0:1], s[70:71], 12
	s_add_u32 s4, s58, s0
	s_addc_u32 s5, s59, s1
	v_and_b32_e32 v80, 1, v210
	v_lshlrev_b32_e32 v192, 1, v209
	v_cmp_eq_u32_e64 s[0:1], 0, v80
	v_lshl_add_u64 v[80:81], s[4:5], 0, v[192:193]
	v_lshlrev_b32_e32 v192, 14, v208
	v_lshl_add_u64 v[80:81], v[80:81], 0, v[192:193]
	s_waitcnt lgkmcnt(0)
	v_rcp_f32_e32 v76, v76
	v_rcp_f32_e32 v77, v77
	v_rcp_f32_e32 v78, v78
	v_rcp_f32_e32 v79, v79
	v_rcp_f32_e32 v72, v72
	v_rcp_f32_e32 v73, v73
	v_rcp_f32_e32 v74, v74
	v_rcp_f32_e32 v75, v75
	v_rcp_f32_e32 v68, v68
	v_rcp_f32_e32 v69, v69
	v_rcp_f32_e32 v70, v70
	v_rcp_f32_e32 v71, v71
	v_rcp_f32_e32 v64, v64
	v_rcp_f32_e32 v65, v65
	v_rcp_f32_e32 v66, v66
	v_rcp_f32_e32 v67, v67
	s_nop 0
	v_mul_f32_e32 v32, v32, v76
	v_mul_f32_e32 v48, v48, v76
	v_mul_f32_e32 v16, v16, v76
	v_mul_f32_e32 v0, v0, v76
	v_mul_f32_e32 v33, v33, v77
	v_mul_f32_e32 v49, v49, v77
	v_mul_f32_e32 v17, v17, v77
	v_mul_f32_e32 v1, v1, v77
	v_mul_f32_e32 v34, v34, v78
	v_mul_f32_e32 v50, v50, v78
	v_mul_f32_e32 v18, v18, v78
	v_mul_f32_e32 v2, v2, v78
	v_mul_f32_e32 v35, v35, v79
	v_mul_f32_e32 v51, v51, v79
	v_mul_f32_e32 v19, v19, v79
	v_mul_f32_e32 v3, v3, v79
	v_mul_f32_e32 v36, v36, v72
	v_mul_f32_e32 v52, v52, v72
	v_mul_f32_e32 v20, v20, v72
	v_mul_f32_e32 v4, v4, v72
	v_mul_f32_e32 v37, v37, v73
	v_mul_f32_e32 v53, v53, v73
	v_mul_f32_e32 v21, v21, v73
	v_mul_f32_e32 v5, v5, v73
	v_mul_f32_e32 v38, v38, v74
	v_mul_f32_e32 v54, v54, v74
	v_mul_f32_e32 v22, v22, v74
	v_mul_f32_e32 v6, v6, v74
	v_mul_f32_e32 v39, v39, v75
	v_mul_f32_e32 v55, v55, v75
	v_mul_f32_e32 v23, v23, v75
	v_mul_f32_e32 v7, v7, v75
	v_mul_f32_e32 v40, v40, v68
	v_mul_f32_e32 v56, v56, v68
	v_mul_f32_e32 v24, v24, v68
	v_mul_f32_e32 v8, v8, v68
	v_mul_f32_e32 v41, v41, v69
	v_mul_f32_e32 v57, v57, v69
	v_mul_f32_e32 v25, v25, v69
	v_mul_f32_e32 v9, v9, v69
	v_mul_f32_e32 v42, v42, v70
	v_mul_f32_e32 v58, v58, v70
	v_mul_f32_e32 v26, v26, v70
	v_mul_f32_e32 v10, v10, v70
	v_mul_f32_e32 v43, v43, v71
	v_mul_f32_e32 v59, v59, v71
	v_mul_f32_e32 v27, v27, v71
	v_mul_f32_e32 v11, v11, v71
	v_mul_f32_e32 v44, v44, v64
	v_mul_f32_e32 v60, v60, v64
	v_mul_f32_e32 v28, v28, v64
	v_mul_f32_e32 v12, v12, v64
	v_mul_f32_e32 v45, v45, v65
	v_mul_f32_e32 v61, v61, v65
	v_mul_f32_e32 v29, v29, v65
	v_mul_f32_e32 v13, v13, v65
	v_mul_f32_e32 v46, v46, v66
	v_mul_f32_e32 v62, v62, v66
	v_mul_f32_e32 v30, v30, v66
	v_mul_f32_e32 v14, v14, v66
	v_mul_f32_e32 v47, v47, v67
	v_mul_f32_e32 v63, v63, v67
	v_mul_f32_e32 v31, v31, v67
	v_mul_f32_e32 v15, v15, v67
	s_nop 1
	v_mov_b32_dpp v88, v32 quad_perm:[1,0,3,2] row_mask:0xf bank_mask:0xf
	v_cvt_pk_bf16_f32 v32, v32, v88
	v_mov_b32_dpp v89, v48 quad_perm:[1,0,3,2] row_mask:0xf bank_mask:0xf
	v_cvt_pk_bf16_f32 v48, v48, v89
	v_mov_b32_dpp v90, v16 quad_perm:[1,0,3,2] row_mask:0xf bank_mask:0xf
	v_cvt_pk_bf16_f32 v16, v16, v90
	v_mov_b32_dpp v91, v0 quad_perm:[1,0,3,2] row_mask:0xf bank_mask:0xf
	v_cvt_pk_bf16_f32 v0, v0, v91
	v_mov_b32_dpp v92, v33 quad_perm:[1,0,3,2] row_mask:0xf bank_mask:0xf
	v_cvt_pk_bf16_f32 v33, v33, v92
	v_mov_b32_dpp v93, v49 quad_perm:[1,0,3,2] row_mask:0xf bank_mask:0xf
	v_cvt_pk_bf16_f32 v49, v49, v93
	v_mov_b32_dpp v94, v17 quad_perm:[1,0,3,2] row_mask:0xf bank_mask:0xf
	v_cvt_pk_bf16_f32 v17, v17, v94
	v_mov_b32_dpp v95, v1 quad_perm:[1,0,3,2] row_mask:0xf bank_mask:0xf
	v_cvt_pk_bf16_f32 v1, v1, v95
	v_mov_b32_dpp v88, v34 quad_perm:[1,0,3,2] row_mask:0xf bank_mask:0xf
	v_cvt_pk_bf16_f32 v34, v34, v88
	v_mov_b32_dpp v89, v50 quad_perm:[1,0,3,2] row_mask:0xf bank_mask:0xf
	v_cvt_pk_bf16_f32 v50, v50, v89
	v_mov_b32_dpp v90, v18 quad_perm:[1,0,3,2] row_mask:0xf bank_mask:0xf
	v_cvt_pk_bf16_f32 v18, v18, v90
	v_mov_b32_dpp v91, v2 quad_perm:[1,0,3,2] row_mask:0xf bank_mask:0xf
	v_cvt_pk_bf16_f32 v2, v2, v91
	v_mov_b32_dpp v92, v35 quad_perm:[1,0,3,2] row_mask:0xf bank_mask:0xf
	v_cvt_pk_bf16_f32 v35, v35, v92
	v_mov_b32_dpp v93, v51 quad_perm:[1,0,3,2] row_mask:0xf bank_mask:0xf
	v_cvt_pk_bf16_f32 v51, v51, v93
	v_mov_b32_dpp v94, v19 quad_perm:[1,0,3,2] row_mask:0xf bank_mask:0xf
	v_cvt_pk_bf16_f32 v19, v19, v94
	v_mov_b32_dpp v95, v3 quad_perm:[1,0,3,2] row_mask:0xf bank_mask:0xf
	v_cvt_pk_bf16_f32 v3, v3, v95
	v_mov_b32_dpp v88, v36 quad_perm:[1,0,3,2] row_mask:0xf bank_mask:0xf
	v_cvt_pk_bf16_f32 v36, v36, v88
	v_mov_b32_dpp v89, v52 quad_perm:[1,0,3,2] row_mask:0xf bank_mask:0xf
	v_cvt_pk_bf16_f32 v52, v52, v89
	v_mov_b32_dpp v90, v20 quad_perm:[1,0,3,2] row_mask:0xf bank_mask:0xf
	v_cvt_pk_bf16_f32 v20, v20, v90
	v_mov_b32_dpp v91, v4 quad_perm:[1,0,3,2] row_mask:0xf bank_mask:0xf
	v_cvt_pk_bf16_f32 v4, v4, v91
	v_mov_b32_dpp v92, v37 quad_perm:[1,0,3,2] row_mask:0xf bank_mask:0xf
	v_cvt_pk_bf16_f32 v37, v37, v92
	v_mov_b32_dpp v93, v53 quad_perm:[1,0,3,2] row_mask:0xf bank_mask:0xf
	v_cvt_pk_bf16_f32 v53, v53, v93
	v_mov_b32_dpp v94, v21 quad_perm:[1,0,3,2] row_mask:0xf bank_mask:0xf
	v_cvt_pk_bf16_f32 v21, v21, v94
	v_mov_b32_dpp v95, v5 quad_perm:[1,0,3,2] row_mask:0xf bank_mask:0xf
	v_cvt_pk_bf16_f32 v5, v5, v95
	v_mov_b32_dpp v88, v38 quad_perm:[1,0,3,2] row_mask:0xf bank_mask:0xf
	v_cvt_pk_bf16_f32 v38, v38, v88
	v_mov_b32_dpp v89, v54 quad_perm:[1,0,3,2] row_mask:0xf bank_mask:0xf
	v_cvt_pk_bf16_f32 v54, v54, v89
	v_mov_b32_dpp v90, v22 quad_perm:[1,0,3,2] row_mask:0xf bank_mask:0xf
	v_cvt_pk_bf16_f32 v22, v22, v90
	v_mov_b32_dpp v91, v6 quad_perm:[1,0,3,2] row_mask:0xf bank_mask:0xf
	v_cvt_pk_bf16_f32 v6, v6, v91
	v_mov_b32_dpp v92, v39 quad_perm:[1,0,3,2] row_mask:0xf bank_mask:0xf
	v_cvt_pk_bf16_f32 v39, v39, v92
	v_mov_b32_dpp v93, v55 quad_perm:[1,0,3,2] row_mask:0xf bank_mask:0xf
	v_cvt_pk_bf16_f32 v55, v55, v93
	v_mov_b32_dpp v94, v23 quad_perm:[1,0,3,2] row_mask:0xf bank_mask:0xf
	v_cvt_pk_bf16_f32 v23, v23, v94
	v_mov_b32_dpp v95, v7 quad_perm:[1,0,3,2] row_mask:0xf bank_mask:0xf
	v_cvt_pk_bf16_f32 v7, v7, v95
	v_mov_b32_dpp v88, v40 quad_perm:[1,0,3,2] row_mask:0xf bank_mask:0xf
	v_cvt_pk_bf16_f32 v40, v40, v88
	v_mov_b32_dpp v89, v56 quad_perm:[1,0,3,2] row_mask:0xf bank_mask:0xf
	v_cvt_pk_bf16_f32 v56, v56, v89
	v_mov_b32_dpp v90, v24 quad_perm:[1,0,3,2] row_mask:0xf bank_mask:0xf
	v_cvt_pk_bf16_f32 v24, v24, v90
	v_mov_b32_dpp v91, v8 quad_perm:[1,0,3,2] row_mask:0xf bank_mask:0xf
	v_cvt_pk_bf16_f32 v8, v8, v91
	v_mov_b32_dpp v92, v41 quad_perm:[1,0,3,2] row_mask:0xf bank_mask:0xf
	v_cvt_pk_bf16_f32 v41, v41, v92
	v_mov_b32_dpp v93, v57 quad_perm:[1,0,3,2] row_mask:0xf bank_mask:0xf
	v_cvt_pk_bf16_f32 v57, v57, v93
	v_mov_b32_dpp v94, v25 quad_perm:[1,0,3,2] row_mask:0xf bank_mask:0xf
	v_cvt_pk_bf16_f32 v25, v25, v94
	v_mov_b32_dpp v95, v9 quad_perm:[1,0,3,2] row_mask:0xf bank_mask:0xf
	v_cvt_pk_bf16_f32 v9, v9, v95
	v_mov_b32_dpp v88, v42 quad_perm:[1,0,3,2] row_mask:0xf bank_mask:0xf
	v_cvt_pk_bf16_f32 v42, v42, v88
	v_mov_b32_dpp v89, v58 quad_perm:[1,0,3,2] row_mask:0xf bank_mask:0xf
	v_cvt_pk_bf16_f32 v58, v58, v89
	v_mov_b32_dpp v90, v26 quad_perm:[1,0,3,2] row_mask:0xf bank_mask:0xf
	v_cvt_pk_bf16_f32 v26, v26, v90
	v_mov_b32_dpp v91, v10 quad_perm:[1,0,3,2] row_mask:0xf bank_mask:0xf
	v_cvt_pk_bf16_f32 v10, v10, v91
	v_mov_b32_dpp v92, v43 quad_perm:[1,0,3,2] row_mask:0xf bank_mask:0xf
	v_cvt_pk_bf16_f32 v43, v43, v92
	v_mov_b32_dpp v93, v59 quad_perm:[1,0,3,2] row_mask:0xf bank_mask:0xf
	v_cvt_pk_bf16_f32 v59, v59, v93
	v_mov_b32_dpp v94, v27 quad_perm:[1,0,3,2] row_mask:0xf bank_mask:0xf
	v_cvt_pk_bf16_f32 v27, v27, v94
	v_mov_b32_dpp v95, v11 quad_perm:[1,0,3,2] row_mask:0xf bank_mask:0xf
	v_cvt_pk_bf16_f32 v11, v11, v95
	v_mov_b32_dpp v88, v44 quad_perm:[1,0,3,2] row_mask:0xf bank_mask:0xf
	v_cvt_pk_bf16_f32 v44, v44, v88
	v_mov_b32_dpp v89, v60 quad_perm:[1,0,3,2] row_mask:0xf bank_mask:0xf
	v_cvt_pk_bf16_f32 v60, v60, v89
	v_mov_b32_dpp v90, v28 quad_perm:[1,0,3,2] row_mask:0xf bank_mask:0xf
	v_cvt_pk_bf16_f32 v28, v28, v90
	v_mov_b32_dpp v91, v12 quad_perm:[1,0,3,2] row_mask:0xf bank_mask:0xf
	v_cvt_pk_bf16_f32 v12, v12, v91
	v_mov_b32_dpp v92, v45 quad_perm:[1,0,3,2] row_mask:0xf bank_mask:0xf
	v_cvt_pk_bf16_f32 v45, v45, v92
	v_mov_b32_dpp v93, v61 quad_perm:[1,0,3,2] row_mask:0xf bank_mask:0xf
	v_cvt_pk_bf16_f32 v61, v61, v93
	v_mov_b32_dpp v94, v29 quad_perm:[1,0,3,2] row_mask:0xf bank_mask:0xf
	v_cvt_pk_bf16_f32 v29, v29, v94
	v_mov_b32_dpp v95, v13 quad_perm:[1,0,3,2] row_mask:0xf bank_mask:0xf
	v_cvt_pk_bf16_f32 v13, v13, v95
	v_mov_b32_dpp v88, v46 quad_perm:[1,0,3,2] row_mask:0xf bank_mask:0xf
	v_cvt_pk_bf16_f32 v46, v46, v88
	v_mov_b32_dpp v89, v62 quad_perm:[1,0,3,2] row_mask:0xf bank_mask:0xf
	v_cvt_pk_bf16_f32 v62, v62, v89
	v_mov_b32_dpp v90, v30 quad_perm:[1,0,3,2] row_mask:0xf bank_mask:0xf
	v_cvt_pk_bf16_f32 v30, v30, v90
	v_mov_b32_dpp v91, v14 quad_perm:[1,0,3,2] row_mask:0xf bank_mask:0xf
	v_cvt_pk_bf16_f32 v14, v14, v91
	v_mov_b32_dpp v92, v47 quad_perm:[1,0,3,2] row_mask:0xf bank_mask:0xf
	v_cvt_pk_bf16_f32 v47, v47, v92
	v_mov_b32_dpp v93, v63 quad_perm:[1,0,3,2] row_mask:0xf bank_mask:0xf
	v_cvt_pk_bf16_f32 v63, v63, v93
	v_mov_b32_dpp v94, v31 quad_perm:[1,0,3,2] row_mask:0xf bank_mask:0xf
	v_cvt_pk_bf16_f32 v31, v31, v94
	v_mov_b32_dpp v95, v15 quad_perm:[1,0,3,2] row_mask:0xf bank_mask:0xf
	v_cvt_pk_bf16_f32 v15, v15, v95
	s_and_saveexec_b64 s[4:5], s[0:1]
	global_store_dword v[80:81], v32, off
	global_store_dword v[80:81], v48, off offset:64
	global_store_dword v[80:81], v16, off offset:128
	global_store_dword v[80:81], v0, off offset:192
	s_mov_b64 s[98:99], 0x1000
	v_lshl_add_u64 v[84:85], v[80:81], 0, s[98:99]
	global_store_dword v[84:85], v33, off
	global_store_dword v[84:85], v49, off offset:64
	global_store_dword v[84:85], v17, off offset:128
	global_store_dword v[84:85], v1, off offset:192
	s_mov_b64 s[98:99], 0x2000
	v_lshl_add_u64 v[86:87], v[80:81], 0, s[98:99]
	global_store_dword v[86:87], v34, off
	global_store_dword v[86:87], v50, off offset:64
	global_store_dword v[86:87], v18, off offset:128
	global_store_dword v[86:87], v2, off offset:192
	s_mov_b64 s[98:99], 0x3000
	v_lshl_add_u64 v[84:85], v[80:81], 0, s[98:99]
	global_store_dword v[84:85], v35, off
	global_store_dword v[84:85], v51, off offset:64
	global_store_dword v[84:85], v19, off offset:128
	global_store_dword v[84:85], v3, off offset:192
	s_mov_b64 s[98:99], 0x8000
	v_lshl_add_u64 v[86:87], v[80:81], 0, s[98:99]
	global_store_dword v[86:87], v36, off
	global_store_dword v[86:87], v52, off offset:64
	global_store_dword v[86:87], v20, off offset:128
	global_store_dword v[86:87], v4, off offset:192
	s_mov_b64 s[98:99], 0x9000
	v_lshl_add_u64 v[84:85], v[80:81], 0, s[98:99]
	global_store_dword v[84:85], v37, off
	global_store_dword v[84:85], v53, off offset:64
	global_store_dword v[84:85], v21, off offset:128
	global_store_dword v[84:85], v5, off offset:192
	s_mov_b64 s[98:99], 0xa000
	v_lshl_add_u64 v[86:87], v[80:81], 0, s[98:99]
	global_store_dword v[86:87], v38, off
	global_store_dword v[86:87], v54, off offset:64
	global_store_dword v[86:87], v22, off offset:128
	global_store_dword v[86:87], v6, off offset:192
	s_mov_b64 s[98:99], 0xb000
	v_lshl_add_u64 v[84:85], v[80:81], 0, s[98:99]
	global_store_dword v[84:85], v39, off
	global_store_dword v[84:85], v55, off offset:64
	global_store_dword v[84:85], v23, off offset:128
	global_store_dword v[84:85], v7, off offset:192
	s_mov_b64 s[98:99], 0x10000
	v_lshl_add_u64 v[86:87], v[80:81], 0, s[98:99]
	global_store_dword v[86:87], v40, off
	global_store_dword v[86:87], v56, off offset:64
	global_store_dword v[86:87], v24, off offset:128
	global_store_dword v[86:87], v8, off offset:192
	s_mov_b64 s[98:99], 0x11000
	v_lshl_add_u64 v[84:85], v[80:81], 0, s[98:99]
	global_store_dword v[84:85], v41, off
	global_store_dword v[84:85], v57, off offset:64
	global_store_dword v[84:85], v25, off offset:128
	global_store_dword v[84:85], v9, off offset:192
	s_mov_b64 s[98:99], 0x12000
	v_lshl_add_u64 v[86:87], v[80:81], 0, s[98:99]
	global_store_dword v[86:87], v42, off
	global_store_dword v[86:87], v58, off offset:64
	global_store_dword v[86:87], v26, off offset:128
	global_store_dword v[86:87], v10, off offset:192
	s_mov_b64 s[98:99], 0x13000
	v_lshl_add_u64 v[84:85], v[80:81], 0, s[98:99]
	global_store_dword v[84:85], v43, off
	global_store_dword v[84:85], v59, off offset:64
	global_store_dword v[84:85], v27, off offset:128
	global_store_dword v[84:85], v11, off offset:192
	s_mov_b64 s[98:99], 0x18000
	v_lshl_add_u64 v[86:87], v[80:81], 0, s[98:99]
	global_store_dword v[86:87], v44, off
	global_store_dword v[86:87], v60, off offset:64
	global_store_dword v[86:87], v28, off offset:128
	global_store_dword v[86:87], v12, off offset:192
	s_mov_b64 s[98:99], 0x19000
	v_lshl_add_u64 v[84:85], v[80:81], 0, s[98:99]
	global_store_dword v[84:85], v45, off
	global_store_dword v[84:85], v61, off offset:64
	global_store_dword v[84:85], v29, off offset:128
	global_store_dword v[84:85], v13, off offset:192
	s_mov_b64 s[98:99], 0x1a000
	v_lshl_add_u64 v[86:87], v[80:81], 0, s[98:99]
	global_store_dword v[86:87], v46, off
	global_store_dword v[86:87], v62, off offset:64
	global_store_dword v[86:87], v30, off offset:128
	global_store_dword v[86:87], v14, off offset:192
	s_mov_b64 s[98:99], 0x1b000
	v_lshl_add_u64 v[84:85], v[80:81], 0, s[98:99]
	global_store_dword v[84:85], v47, off
	global_store_dword v[84:85], v63, off offset:64
	global_store_dword v[84:85], v31, off offset:128
	global_store_dword v[84:85], v15, off offset:192
	s_branch .LBB0_209
